# v9 + layer-1 weight copies split into 288 equal shares over CUs 32..255 (w_in halves / w_out+w_kv per 64-CU group, whole virtual CU on 224..255); freed in-projection units go to CUs 160..223 as ninth
# speedup vs baseline: 1.0040x; 1.0040x over previous
; #define LAS __attribute__((address_space(3)))
; #define P (*({ CParams* q_ = kp; asm volatile("" : "+s"(q_)); q_; }))
; #define wave (__builtin_amdgcn_readfirstlane(tid >> 6))
; DI void ret_unit(CParams& P, int l, int u, LAS unsigned char* lds, int tid_, int lane_, int wave_) {
;     ...
;     const int hh = u & 3, b = u >> 2;
;     constexpr int LD = 264, LDP = 72, LDR = 256, IMG = 33792;
;     LAS bf16_t* Qs = (LAS bf16_t*)lds; LAS bf16_t* Ks = (LAS bf16_t*)(lds + IMG); LAS bf16_t* Vs = (LAS bf16_t*)(lds + 2 * IMG);
;     LAS bf16_t* Ps = (LAS bf16_t*)(lds + 3 * IMG); LAS bf16_t* R = (LAS bf16_t*)(lds + 3 * IMG + 9216);
;     const float g64 = exp2f(64.f * log2f(1.f - exp2f(-5.f - (float)hh)));
; __global__ void __launch_bounds__(NTHREADS, 2) fwd_megakernel(Params P_) {
;     ...
;         const float* rss_in = (const float*)(ws + (l == 0 ? WS_RSS0 : WS_RSS1));
;         float* rss_out = (float*)(ws + (l == 0 ? WS_RSS1 : WS_RSS2));
;         const pg8::Gemm g_in{(const bf16_t*)(ws + WS_XB), (const bf16_t*)(ws + WS_WIN) + (size_t)l * NPROJ * DM, MTOK, NPROJ, DM};
;         const pg8::EpiProj E_in{(bf16_t*)(ws + WS_PROJ), NPROJ, rss_in, 1.f / DM, EPS, 1, (const float*)(ws + WS_COS), (const float*)(ws + WS_SIN), (float*)(ws + WS_AVSTAT) + (size_t)l * MTOK * 2};
;         { const pg8::SubOrder S{16, 1024, 16, 24, 24, bx, G, 0};
;           pg8::gemm_phase<pg8::EpiProj, pg8::SubOrder, true, true>(lds, g_in, S, E_in); }
;         xcd_barrier(xbar);
;     ...
;         if (bx < 32) ret_unit(P, l, bx, lds, tid, lane, wave);
;     ...
;         { const pg8::SubOrder S{32, 2048, 24, 0, 16, bx, G, 1};
;           pg8::gemm_phase<pg8::EpiProj, pg8::SubOrder, true, true>(lds, g_in, S, E_in); }
;         { pg8::Gemm g{(const bf16_t*)(ws + WS_MEMB), (const bf16_t*)(ws + WS_WKV) + (size_t)l * NKV * DM, MROWS, NKV, DM}; pg8::StaticOrder S; S.init(MROWS, NKV, G, (bx >= 96 && bx < 160) ? bx - 96 : (1 << 20));
.LBB0_248:
	v_writelane_b32 v254, s42, 3
	s_nop 1
	v_writelane_b32 v254, s43, 4
	s_or_b64 exec, exec, s[38:39]
	s_add_u32 s50, s72, 0x12200000
	s_addc_u32 s51, s73, 0
	s_add_u32 s80, s72, 0x200000
	s_addc_u32 s83, s73, 0
	s_add_u32 s52, s72, 0x1a200000
	s_addc_u32 s53, s73, 0
	s_add_u32 s0, s72, 0x3ba00000
	s_addc_u32 s1, s73, 0
	v_writelane_b32 v254, s0, 5
	s_mov_b32 s33, 0xc2fc0000
	v_mov_b32_e32 v219, 0x42800000
	v_writelane_b32 v254, s1, 6
	s_add_u32 s0, s72, 0x3c200000
	s_addc_u32 s1, s73, 0
	s_add_u32 s88, s72, 0x40000
	s_addc_u32 s89, s73, 0
	s_cmpk_lt_i32 s69, 0x400
	v_writelane_b32 v254, s0, 7
	s_cselect_b64 s[8:9], -1, 0
	s_ashr_i32 s92, s69, 31
	v_writelane_b32 v254, s1, 8
	s_lshr_b32 s0, s92, 29
	s_add_i32 s2, s69, s0
	s_ashr_i32 s4, s2, 3
	s_lshl_b32 s0, s69, 7
	s_mul_i32 s1, s4, 0xfffffc01
	s_add_i32 s0, s1, s0
	s_ashr_i32 s1, s0, 31
	s_lshr_b32 s1, s1, 25
	s_add_i32 s1, s0, s1
	s_ashr_i32 s5, s1, 7
	s_and_b32 s1, s1, 0xffffff80
	s_sub_i32 s0, s0, s1
	s_bfe_i32 s1, s0, 0x80000
	s_bfe_u32 s1, s1, 0x3000c
	s_add_i32 s1, s0, s1
	s_bfe_i32 s6, s1, 0x80000
	s_and_b32 s6, 0xffff, s6
	s_and_b32 s1, s1, 0xf8
	s_lshr_b32 s6, s6, 3
	s_sub_i32 s0, s0, s1
	s_lshl_b32 s5, s5, 3
	s_sext_i32_i8 s0, s0
	s_add_i32 s6, s6, 24
	s_add_i32 s10, s5, s0
	s_and_b32 s6, s6, 0xff
	s_cmp_lt_i32 s69, 32
	s_cselect_b64 s[0:1], -1, 0
	s_and_b32 s5, s69, 3
	v_cvt_f32_ubyte0_e32 v0, s5
	v_sub_f32_e32 v0, 0xc0a00000, v0
	v_cmp_gt_f32_e32 vcc, s33, v0
	v_writelane_b32 v254, s0, 9
	s_mov_b32 s45, 0x800000
	v_cndmask_b32_e32 v1, 0, v219, vcc
	v_add_f32_e32 v0, v0, v1
	v_exp_f32_e32 v0, v0
	v_writelane_b32 v254, s1, 10
	s_and_b64 s[0:1], vcc, exec
	s_cselect_b32 s0, 0xffffffc0, 0
	v_ldexp_f32 v0, v0, s0
	v_sub_f32_e32 v0, 1.0, v0
	v_cmp_gt_f32_e32 vcc, s45, v0
	s_and_b64 s[0:1], vcc, exec
	s_cselect_b32 s0, 32, 0
	v_ldexp_f32 v0, v0, s0
	v_log_f32_e32 v0, v0
	v_mov_b32_e32 v220, 0x42000000
	v_cndmask_b32_e32 v1, 0, v220, vcc
	s_mul_i32 s0, s77, s76
	v_sub_f32_e32 v0, v0, v1
	v_mul_f32_e32 v1, 0x42800000, v0
	v_cmp_gt_f32_e32 vcc, s33, v1
	s_lshl_b32 s7, s5, 8
	s_mul_i32 s77, s0, s3
	v_cndmask_b32_e32 v1, 0, v219, vcc
	v_fmac_f32_e32 v1, 0x42800000, v0
	v_exp_f32_e32 v0, v1
	s_and_b64 s[0:1], vcc, exec
	s_cselect_b32 s0, 0xffffffc0, 0
	s_mov_b32 s97, 0
	v_ldexp_f32 v192, v0, s0
	s_lshl_b32 s0, s69, 9
	s_and_b32 s0, s0, 0xfffff800
	v_writelane_b32 v254, s0, 11
	s_cmp_gt_i32 s69, 31
	s_movk_i32 s0, 0xffe0
	s_cselect_b32 s0, s0, 0x700
	s_add_i32 s0, s0, s69
	s_ashr_i32 s1, s0, 31
	s_lshr_b32 s1, s1, 29
	s_add_i32 s1, s0, s1
	s_ashr_i32 s1, s1, 3
	s_lshl_b32 s0, s0, 8
	s_mulk_i32 s1, 0xf801
	s_add_i32 s0, s1, s0
	s_ashr_i32 s1, s0, 31
	s_lshr_b32 s1, s1, 24
	s_add_i32 s1, s0, s1
	s_ashr_i32 s3, s1, 8
	s_and_b32 s1, s1, 0xffffff00
	s_sub_i32 s0, s0, s1
	s_bfe_u32 s1, s0, 0x3001c
	s_add_i32 s1, s0, s1
	s_sext_i32_i16 s5, s1
	s_and_b32 s1, s1, 0xfff8
	s_sub_i32 s1, s0, s1
	s_lshl_b32 s3, s3, 3
	s_sext_i32_i16 s1, s1
	s_ashr_i32 s5, s5, 3
	s_add_i32 s12, s3, s1
	s_cmpk_lt_i32 s0, 0xc0
	s_cselect_b32 s0, 0, 16
	s_add_i32 s14, s0, s5
	s_mov_b32 s0, s12
	s_ashr_i32 s13, s12, 31
	v_writelane_b32 v254, s0, 12
	s_ashr_i32 s15, s14, 31
	v_mov_b32_e32 v0, 0x60
	v_writelane_b32 v254, s1, 13
	s_lshl_b64 s[0:1], s[12:13], 21
	s_mov_b32 s12, s14
	v_writelane_b32 v254, s12, 14
	s_movk_i32 s55, 0x6000
	v_mov_b32_e32 v194, v192
	v_writelane_b32 v254, s13, 15
	s_lshl_b64 s[12:13], s[14:15], 21
	v_writelane_b32 v254, s12, 16
	s_add_u32 s0, s50, s0
	s_addc_u32 s1, s51, s1
	v_writelane_b32 v254, s13, 17
	s_add_u32 s12, s0, 0x100000
	v_writelane_b32 v254, s0, 18
	s_addc_u32 s13, s1, 0
	v_mov_b32_e32 v195, v192
	v_writelane_b32 v254, s1, 19
	v_writelane_b32 v254, s12, 20
	s_add_i32 s0, s69, 0x700
	s_movk_i32 s81, 0x2000
	v_writelane_b32 v254, s13, 21
	v_writelane_b32 v254, s0, 22
	v_sub_co_u32_e64 v0, s[0:1], s69, v0
	s_nop 0
	v_readfirstlane_b32 s3, v0
	v_writelane_b32 v254, s0, 23
	v_mov_b32_e32 v197, 0
	v_mov_b32_e32 v222, 0x358637bd
	v_writelane_b32 v254, s1, 24
	s_add_i32 s0, s69, 0x7a0
	v_writelane_b32 v254, s0, 25
	s_sub_i32 s0, s69, 32
	s_add_u32 s5, s72, 0x3a200000
	s_addc_u32 s11, s73, 0
	v_writelane_b32 v254, s0, 26
	s_add_u32 s0, s72, 0x10200000
	v_writelane_b32 v254, s0, 27
	s_addc_u32 s0, s73, 0
	s_cmp_lt_u32 s3, 64
	v_writelane_b32 v254, s0, 28
	s_cselect_b64 s[0:1], -1, 0
; #define P (*({ CParams* q_ = kp; asm volatile("" : "+s"(q_)); q_; }))
; __global__ void __launch_bounds__(NTHREADS, 2) fwd_megakernel(Params P_) {
;     ...
;         { pg8::Gemm g{(const bf16_t*)(ws + WS_MEMB), (const bf16_t*)(ws + WS_WKV) + (size_t)l * NKV * DM, MROWS, NKV, DM}; pg8::StaticOrder S; S.init(MROWS, NKV, G, (bx >= 96 && bx < 160) ? bx - 96 : (1 << 20));
;           pg8::EpiProj E{(bf16_t*)(ws + WS_KV), NKV, nullptr, 0.f, 0.f, 0, nullptr, nullptr, nullptr};
;           pg8::gemm_phase<pg8::EpiProj, pg8::StaticOrder, true, true>(lds, g, S, E); }
;         if (bx >= 160) { int t2 = threadIdx.x; asm volatile("" : "+v"(t2)); const int w2 = __builtin_amdgcn_readfirstlane(t2 >> 6);
;             convert_weights(P, 1, lds, (bx - 160) * NWAVES + w2, 96 * NWAVES, t2 & 63, w2, l == 0 ? 5 : 2); }
	v_writelane_b32 v254, s0, 29
	v_mov_b32_e32 v223, 1
	s_mov_b32 s84, 0x3e0f83e1
	v_writelane_b32 v254, s1, 30
	s_and_b64 s[0:1], s[0:1], exec
	s_cselect_b32 s1, s3, 0x100000
	s_add_u32 s12, s72, 0x3b200000
	s_addc_u32 s13, s73, 0
	v_writelane_b32 v254, s12, 31
	s_bfe_u32 s3, s1, 0x30003
	s_lshr_b32 s0, s1, 3
	v_writelane_b32 v254, s13, 32
	v_writelane_b32 v254, s3, 33
	v_writelane_b32 v254, s1, 34
	s_and_b32 s1, s1, 7
	v_writelane_b32 v254, s1, 35
	s_lshl_b32 s1, s1, 21
	s_lshl_b32 s0, s0, 21
	v_writelane_b32 v254, s1, 36
	v_writelane_b32 v254, s5, 37
	s_add_u32 s0, s5, s0
	v_writelane_b32 v254, s11, 38
	s_addc_u32 s1, s11, 0
	s_add_u32 s12, s0, 0x100000
	v_writelane_b32 v254, s0, 39
	s_addc_u32 s13, s1, 0
	s_movk_i32 s85, 0xffdf
	v_writelane_b32 v254, s1, 40
	v_writelane_b32 v254, s12, 41
	s_ashr_i32 s0, s76, 31
	s_cmpk_gt_i32 s69, 0x1f
	v_writelane_b32 v254, s13, 42
	v_writelane_b32 v254, s0, 43
	s_cselect_b64 s[0:1], -1, 0
	v_writelane_b32 v254, s0, 44
	v_mov_b32_e32 v224, 0x3d800000
	v_not_b32_e32 v225, 63
	v_writelane_b32 v254, s1, 45
	s_add_i32 s0, s69, 0xffffffe0
	s_and_b32 s0, s0, 63
	s_add_i32 s98, s69, 0xffffff60
	s_cmpk_gt_i32 s69, 0xdf
	s_cselect_b32 s0, s98, s0
	s_lshl_b32 s0, s0, 3
	s_add_u32 s5, s72, 0x32200000
	s_addc_u32 s12, s73, 0
	v_writelane_b32 v254, s0, 46
	s_add_u32 s0, s72, 0xc200000
	v_writelane_b32 v254, s0, 47
	s_addc_u32 s0, s73, 0
	v_writelane_b32 v254, s0, 48
	s_and_b32 s0, s2, -8
	s_sub_i32 s2, s69, s0
	s_mov_b32 s0, s10
	v_writelane_b32 v254, s0, 49
	s_ashr_i32 s11, s10, 31
	s_lshl_b32 s3, s2, 7
	v_writelane_b32 v254, s1, 50
	s_lshl_b64 s[0:1], s[10:11], 21
	v_writelane_b32 v254, s6, 51
	s_lshl_b32 s6, s6, 21
	s_add_u32 s0, s50, s0
	s_addc_u32 s1, s51, s1
	v_writelane_b32 v254, s6, 52
	s_add_u32 s10, s0, 0x100000
	v_writelane_b32 v254, s0, 53
	s_addc_u32 s11, s1, 0
	s_cmp_lt_i32 s2, 0
	s_mulk_i32 s2, 0x81
	v_writelane_b32 v254, s1, 54
	s_cselect_b32 s0, s2, s3
	s_add_i32 s0, s0, s4
	s_ashr_i32 s1, s0, 31
	s_lshr_b32 s1, s1, 25
	s_add_i32 s1, s0, s1
	s_ashr_i32 s2, s1, 7
	s_and_b32 s1, s1, 0xff80
	s_sub_i32 s1, s0, s1
	s_bfe_i32 s0, s1, 0x80000
	s_bfe_u32 s0, s0, 0x3000c
	s_add_i32 s3, s1, s0
	s_bfe_i32 s0, s3, 0x80000
	s_and_b32 s3, s3, 0xf8
	s_sub_i32 s1, s1, s3
	v_writelane_b32 v254, s10, 55
	s_lshl_b32 s2, s2, 3
	s_sext_i32_i16 s4, s0
	s_sext_i32_i8 s1, s1
	v_writelane_b32 v254, s11, 56
	s_add_i32 s10, s2, s1
	s_ashr_i32 s1, s4, 3
	s_lshr_b32 s0, s4, 3
	v_writelane_b32 v254, s1, 57
	s_mov_b32 s2, s10
	v_writelane_b32 v254, s2, 58
	s_bfe_i64 s[0:1], s[0:1], 0x100000
	s_ashr_i32 s11, s10, 31
	v_writelane_b32 v254, s3, 59
	s_lshl_b64 s[0:1], s[0:1], 21
	s_lshl_b64 s[2:3], s[10:11], 21
	v_writelane_b32 v254, s0, 60
	v_mbcnt_hi_u32_b32 v226, -1, v71
	v_mov_b32_e32 v227, 0x840
	v_writelane_b32 v254, s1, 61
	s_add_u32 s0, s5, s2
	s_addc_u32 s1, s12, s3
	s_add_u32 s2, s0, 0x100000
	v_writelane_b32 v255, s0, 0
	s_addc_u32 s3, s1, 0
	v_writelane_b32 v254, s5, 62
	v_writelane_b32 v255, s1, 1
	v_writelane_b32 v255, s2, 2
	s_add_i32 s0, 0, 0x27f20
	v_writelane_b32 v254, s12, 63
	v_writelane_b32 v255, s3, 3
	v_writelane_b32 v255, s8, 4
	s_movk_i32 s93, 0x210
	s_movk_i32 s79, 0x7fff
	v_writelane_b32 v255, s9, 5
	v_writelane_b32 v255, s0, 6
	s_add_i32 s0, 0, 0x27f24
	v_writelane_b32 v255, s0, 7
	s_add_i32 s0, 0, 0x1b000
	v_writelane_b32 v255, s0, 8
	s_add_i32 s0, 0, 0x18c00
	v_writelane_b32 v255, s0, 9
	v_writelane_b32 v255, s7, 10
	v_writelane_b32 v255, s72, 11
	v_cndmask_b32_e64 v221, 0, 1, s[8:9]
	s_lshl_b32 s16, s7, 1
	v_writelane_b32 v255, s73, 12
	v_writelane_b32 v255, s74, 13
	s_mov_b32 s57, 0x32201000
	s_movk_i32 s43, 0x1000
	v_writelane_b32 v255, s75, 14
	v_writelane_b32 v255, s69, 15
	v_writelane_b32 v255, s76, 16
	s_mov_b32 s70, 0x1a202000
	s_mov_b32 s71, 0x32200000
	v_writelane_b32 v255, s77, 17
	v_writelane_b32 v255, s78, 18
	v_writelane_b32 v255, s86, 19
	s_movk_i32 s56, 0x110
	s_add_i32 s4, 0, 0x11000
	v_writelane_b32 v255, s87, 20
	v_writelane_b32 v255, s80, 21
	v_writelane_b32 v255, s83, 22
	v_writelane_b32 v255, s88, 23
	v_writelane_b32 v255, s89, 24
	v_writelane_b32 v255, s92, 25
	s_movk_i32 s5, 0x5000
	s_mov_b64 s[0:1], -1
	s_mov_b64 s[60:61], 0x80
	s_mov_b32 s82, 0x3a800000
	s_mov_b32 s62, s97
	v_writelane_b32 v255, s77, 26
	s_waitcnt lgkmcnt(0)
	s_barrier
	s_branch .LBB0_251

;     __device__ __forceinline__ bool next(int i, Unit& u) const {
;         int L;
;         if (mode == 0) { L = i * G + c; if (L >= nwg) return false; }
;         else if (c >= 32) { if (i < 8) L = i * 224 + (c - 32); else if (i == 8 && c < 96) L = 1984 + (c - 32); else return false; }
;         else { if (i < 6) L = 1792 + i * 32 + c; else return false; }
;         int wgid = L; { const int q = nwg / NXCD, xcd = wgid % NXCD, off = wgid / NXCD; wgid = xcd * q + off; }
;         const int nig = WGM * nNv, gid = wgid / nig; const int pv = (wgid % nig) / WGM;
;         u.pm = gid * WGM + ((wgid % nig) % WGM); u.pn = pv < split ? pv + off0 : pv + off1; return true;
.LBB0_416:
	s_and_b64 vcc, exec, s[26:27]
	s_cbranch_vccz .LBB0_421
	s_cmp_gt_u32 s2, 6
	s_mov_b64 s[26:27], -1
	s_cbranch_scc0 .LBB0_419
	s_cmp_eq_u32 s40, 8
	v_readlane_b32 s14, v254, 23
	s_cselect_b64 s[2:3], -1, 0
	v_readlane_b32 s15, v254, 24
	s_and_b64 s[14:15], s[14:15], s[2:3]
	s_mov_b64 s[26:27], 0
	v_readlane_b32 s3, v254, 25
	s_cmp_eq_u32 s40, 8
	s_cbranch_scc0 .LBB0_421
	s_cmp_ge_u32 s69, 160
	s_cbranch_scc0 .LBB0_421
	s_cmp_lt_u32 s69, 224
	s_cbranch_scc0 .LBB0_421
	s_add_i32 s3, s3, -192
	s_mov_b64 s[14:15], -1
	s_branch .LBB0_421

; #define LAS __attribute__((address_space(3)))
; #define P (*({ CParams* q_ = kp; asm volatile("" : "+s"(q_)); q_; }))
; #define wave (__builtin_amdgcn_readfirstlane(tid >> 6))
;     unsigned char* ws = P.ws;
;     LAS float* scr = (LAS float*)(lds + wave * 16384);
;     constexpr int I_IN = (DM / 64) * (NPROJ / 32), I_OUT = (DM / 64) * (DM / 32), I_KV = (DM / 64) * (NKV / 32);
;     if (which & 1) p0_matrix(P.w_in + (size_t)l * DM * NPROJ, P.norm_g + l * DM, DM, NPROJ, (bf16_t*)(ws + WS_WIN) + (size_t)l * NPROJ * DM, scr, I_IN, gw, NGW, lane);
;     if (which & 2) p0_matrix(P.w_out + (size_t)l * DM * DM, nullptr, DM, DM, (bf16_t*)(ws + WS_WOUT) + (size_t)l * DM * DM, scr, I_OUT, gw, NGW, lane);
;     if (which & 4) p0_matrix(P.w_kv + (size_t)l * DM * NKV, P.mem_ng + l * DM, DM, NKV, (bf16_t*)(ws + WS_WKV) + (size_t)l * NKV * DM, scr, I_KV, gw, NGW, lane);
; __global__ void __launch_bounds__(NTHREADS, 2) fwd_megakernel(Params P_) {
;     ...
;         if (bx >= 160) { int t2 = threadIdx.x; asm volatile("" : "+v"(t2)); const int w2 = __builtin_amdgcn_readfirstlane(t2 >> 6);
;             convert_weights(P, 1, lds, (bx - 160) * NWAVES + w2, 96 * NWAVES, t2 & 63, w2, l == 0 ? 5 : 2); }
.LBB0_517:
	v_readlane_b32 s0, v254, 44
	v_readlane_b32 s1, v254, 45
	s_andn2_b64 vcc, exec, s[0:1]
	s_cbranch_vccnz .LBB0_693
	v_mov_b32_e32 v0, v218
	s_mov_b64 s[12:13], s[74:75]
	v_readfirstlane_b32 s0, v0
	s_ashr_i32 s2, s0, 6
	v_readlane_b32 s0, v254, 46
	s_add_i32 s6, s0, s2
	s_load_dwordx2 s[10:11], s[12:13], 0xa0
	s_and_b64 s[0:1], s[94:95], exec
	s_cselect_b32 s1, 7, 0
	s_mov_b32 s98, 0
	s_movk_i32 s99, 0x5400
	s_cmpk_gt_i32 s69, 0xdf
	s_cbranch_scc1 .Lcopy_cls_done
	s_cmpk_gt_i32 s69, 0x9f
	s_cbranch_scc0 .Lcopy_cls_in
	s_and_b32 s1, s1, 6
	s_branch .Lcopy_cls_done
.Lcopy_cls_in:
	s_and_b32 s1, s1, 1
	s_cmpk_gt_i32 s69, 0x5f
	s_cbranch_scc1 .Lcopy_cls_hi
	s_movk_i32 s99, 0x2400
	s_branch .Lcopy_cls_done
.Lcopy_cls_hi:
	s_movk_i32 s98, 0x3000
.Lcopy_cls_done:
	s_mov_b32 s100, s1
	s_lshl_b32 s0, s2, 14
	s_add_i32 s0, s0, 0
	s_bitcmp0_b32 s1, 0
	v_and_b32_e32 v140, 63, v0
	s_cbranch_scc1 .LBB0_598
	s_cmpk_gt_i32 s6, 0x5fff
	s_cbranch_scc1 .LBB0_598
	s_load_dwordx4 s[20:23], s[12:13], 0x18
	v_lshlrev_b32_e32 v0, 4, v140
	v_and_b32_e32 v196, 0x70, v0
	s_mov_b64 s[2:3], 0xc000000
	v_lshrrev_b32_e32 v141, 3, v140
	s_waitcnt lgkmcnt(0)
	v_lshl_add_u64 v[0:1], s[22:23], 0, v[196:197]
	v_lshl_add_u64 v[132:133], v[0:1], 0, s[2:3]
	v_lshlrev_b32_e32 v0, 3, v140
	v_and_b32_e32 v0, 56, v0
	s_add_u32 s14, s20, 0x4000
	v_add_u32_e32 v2, s0, v196
	s_movk_i32 s2, 0x84
	v_lshlrev_b32_e32 v196, 1, v0
	s_addc_u32 s15, s21, 0
	v_mad_u32_u24 v4, v141, s2, v227
	v_mul_u32_u24_e32 v5, 0x84, v0
	v_lshl_add_u64 v[0:1], s[10:11], 0, v[196:197]
	s_mov_b64 s[2:3], 0x6200000
	s_cmp_lg_u64 s[20:21], 0
	v_mul_u32_u24_e32 v3, 0x84, v141
	v_lshl_add_u64 v[134:135], v[0:1], 0, s[2:3]
	v_lshlrev_b32_e32 v0, 2, v141
	s_cselect_b64 s[18:19], -1, 0
	v_or_b32_e32 v142, 8, v141
	v_or_b32_e32 v143, 16, v141
	v_or_b32_e32 v144, 24, v141
	v_or_b32_e32 v145, 32, v141
	v_or_b32_e32 v146, 40, v141
	v_or_b32_e32 v147, 48, v141
	v_or_b32_e32 v148, 56, v141
	v_add3_u32 v149, s0, v5, v0
	s_add_i32 s3, s6, s98
	s_lshl_b32 s2, s3, 5
	v_add_u32_e32 v150, v2, v3
	v_add_u32_e32 v151, v2, v4
	s_branch .LBB0_523

; #define LAS __attribute__((address_space(3)))
; DI void p0_matrix(const float* W, const float* gain, int K, int N, bf16_t* WT, LAS float* scr, int nitems, int gw, int NGW, int lane) {
;     for (int it = gw; it < nitems; it += 4 * NGW) {
;         const int it2 = it + NGW, it3 = it + 2 * NGW, it4 = it + 3 * NGW; const bool h2 = it2 < nitems, h3 = it3 < nitems, h4 = it4 < nitems;
;         f32x4 va[8], vb[8], vc[8], vd[8];
;         p0_item_load(W, N, it, lane, va);
;         if (h2) p0_item_load(W, N, it2, lane, vb);
;         if (h3) p0_item_load(W, N, it3, lane, vc);
;         if (h4) p0_item_load(W, N, it4, lane, vd);
;         p0_item_store(va, gain, K, N, WT, scr, it, lane);
;         if (h2) p0_item_store(vb, gain, K, N, WT, scr, it2, lane);
;         if (h3) p0_item_store(vc, gain, K, N, WT, scr, it3, lane);
;         if (h4) p0_item_store(vd, gain, K, N, WT, scr, it4, lane);
;     }
.LBB0_522:
	s_add_i32 s7, s3, 0xc00
	s_add_i32 s2, s2, 0x18000
	s_cmp_lt_i32 s3, s99
	s_mov_b32 s3, s7
	s_cbranch_scc0 .LBB0_598

; #define LAS __attribute__((address_space(3)))
; #define P (*({ CParams* q_ = kp; asm volatile("" : "+s"(q_)); q_; }))
; #define wave (__builtin_amdgcn_readfirstlane(tid >> 6))
; DI void p0_matrix(const float* W, const float* gain, int K, int N, bf16_t* WT, LAS float* scr, int nitems, int gw, int NGW, int lane) {
;     for (int it = gw; it < nitems; it += 4 * NGW) {
;         const int it2 = it + NGW, it3 = it + 2 * NGW, it4 = it + 3 * NGW; const bool h2 = it2 < nitems, h3 = it3 < nitems, h4 = it4 < nitems;
;         f32x4 va[8], vb[8], vc[8], vd[8];
;         p0_item_load(W, N, it, lane, va);
;         if (h2) p0_item_load(W, N, it2, lane, vb);
;         if (h3) p0_item_load(W, N, it3, lane, vc);
;         if (h4) p0_item_load(W, N, it4, lane, vd);
;         p0_item_store(va, gain, K, N, WT, scr, it, lane);
;         if (h2) p0_item_store(vb, gain, K, N, WT, scr, it2, lane);
;         if (h3) p0_item_store(vc, gain, K, N, WT, scr, it3, lane);
;         if (h4) p0_item_store(vd, gain, K, N, WT, scr, it4, lane);
;     }
; }
;     unsigned char* ws = P.ws;
;     LAS float* scr = (LAS float*)(lds + wave * 16384);
;     constexpr int I_IN = (DM / 64) * (NPROJ / 32), I_OUT = (DM / 64) * (DM / 32), I_KV = (DM / 64) * (NKV / 32);
;     if (which & 1) p0_matrix(P.w_in + (size_t)l * DM * NPROJ, P.norm_g + l * DM, DM, NPROJ, (bf16_t*)(ws + WS_WIN) + (size_t)l * NPROJ * DM, scr, I_IN, gw, NGW, lane);
;     if (which & 2) p0_matrix(P.w_out + (size_t)l * DM * DM, nullptr, DM, DM, (bf16_t*)(ws + WS_WOUT) + (size_t)l * DM * DM, scr, I_OUT, gw, NGW, lane);
;     if (which & 4) p0_matrix(P.w_kv + (size_t)l * DM * NKV, P.mem_ng + l * DM, DM, NKV, (bf16_t*)(ws + WS_WKV) + (size_t)l * NKV * DM, scr, I_KV, gw, NGW, lane);
.LBB0_613:
	s_bitcmp0_b32 s100, 2
	s_cbranch_scc1 .LBB0_693
	s_andn2_b64 vcc, exec, s[94:95]
	s_cbranch_vccnz .LBB0_693
	s_cmpk_gt_i32 s6, 0xfff
	s_cbranch_scc1 .LBB0_693
	s_load_dwordx4 s[20:23], s[12:13], 0x78
	v_lshlrev_b32_e32 v0, 4, v140
	v_and_b32_e32 v196, 0x70, v0
	s_mov_b64 s[2:3], 0x2000000
	v_add_u32_e32 v2, s0, v196
	s_waitcnt lgkmcnt(0)
	v_lshl_add_u64 v[0:1], s[22:23], 0, v[196:197]
	v_lshl_add_u64 v[132:133], v[0:1], 0, s[2:3]
	v_lshlrev_b32_e32 v0, 3, v140
	v_and_b32_e32 v0, 56, v0
	s_add_u32 s12, s20, 0x4000
	v_lshlrev_b32_e32 v196, 1, v0
	v_lshrrev_b32_e32 v141, 3, v140
	s_addc_u32 s13, s21, 0
	s_movk_i32 s1, 0x84
	v_mul_u32_u24_e32 v5, 0x84, v0
	v_lshl_add_u64 v[0:1], s[10:11], 0, v[196:197]
	s_mov_b64 s[2:3], 0x11200000
	s_cmp_lg_u64 s[20:21], 0
	v_mul_u32_u24_e32 v3, 0x84, v141
	v_mad_u32_u24 v4, v141, s1, v227
	v_lshl_add_u64 v[134:135], v[0:1], 0, s[2:3]
	v_lshlrev_b32_e32 v0, 2, v141
	s_cselect_b64 s[14:15], -1, 0
	v_or_b32_e32 v142, 8, v141
	v_or_b32_e32 v143, 16, v141
	v_or_b32_e32 v144, 24, v141
	v_or_b32_e32 v145, 32, v141
	v_or_b32_e32 v146, 40, v141
	v_or_b32_e32 v147, 48, v141
	v_or_b32_e32 v148, 56, v141
	v_add3_u32 v140, s0, v5, v0
	s_lshl_b32 s0, s6, 5
	v_add_u32_e32 v149, v2, v3
	v_add_u32_e32 v150, v2, v4
	s_branch .LBB0_618
